# attention tile loop: the four K/V LDS-DMA issues of computing waves moved from the tile head into the MFMA-only PV tail (guarded by the staging predicate); skipping waves keep the head issue
# speedup vs baseline: 1.0048x; 1.0048x over previous
.LBB0_35:
	s_mov_b32 s59, s60
	s_add_i32 s60, s58, 2
	s_cmp_ge_u32 s60, s56
	s_cselect_b64 s[86:87], -1, 0
	s_and_b64 vcc, exec, s[86:87]
	s_cbranch_vccnz .LBB0_39
	s_cmp_gt_i32 s58, s57
	s_cbranch_scc0 .LBB0_40
	s_add_i32 s60, s27, s61
	v_lshl_add_u64 v[128:129], s[54:55], 0, v[146:147]
	s_mov_b32 m0, s60
	s_nop 0
	global_load_lds_dwordx4 v[128:129], off
	v_lshl_add_u64 v[128:129], s[54:55], 0, v[152:153]
	s_add_i32 m0, s60, 0x4000
	s_nop 0
	global_load_lds_dwordx4 v[128:129], off
	v_lshl_add_u64 v[128:129], s[54:55], 0, v[148:149]
	s_add_i32 m0, s60, 0x400
	s_nop 0
	global_load_lds_dwordx4 v[128:129], off
	v_lshl_add_u64 v[128:129], s[54:55], 0, v[154:155]
	s_add_i32 m0, s60, 0x4400
	s_nop 0
	global_load_lds_dwordx4 v[128:129], off

.LBB0_40:
	s_add_i32 s60, s59, 0
	s_and_b64 vcc, exec, s[86:87]
	v_add_u32_e32 v144, s60, v196
	ds_read_b128 v[188:191], v144
	ds_read_b128 v[200:203], v197
	v_xad_u32 v144, v196, 32, s60
	ds_read_b128 v[204:207], v144
	v_xor_b32_e32 v199, 32, v197
	ds_read_b128 v[216:219], v199
	v_xad_u32 v144, v196, 64, s60
	ds_read_b128 v[220:223], v144
	v_xor_b32_e32 v199, 64, v197
	ds_read_b128 v[224:227], v199
	s_waitcnt lgkmcnt(4)
	v_mfma_f32_32x32x16_bf16 v[128:143], v[188:191], v[200:203], 0
	v_xor_b32_e32 v144, 0x60, v196
	v_add_u32_e32 v144, s60, v144
	ds_read_b128 v[188:191], v144
	v_xor_b32_e32 v199, 0x60, v197
	ds_read_b128 v[200:203], v199
	s_waitcnt lgkmcnt(4)
	v_mfma_f32_32x32x16_bf16 v[128:143], v[204:207], v[216:219], v[128:143]
	v_xor_b32_e32 v144, 0x80, v196
	v_add_u32_e32 v144, s60, v144
	ds_read_b128 v[204:207], v144
	v_xor_b32_e32 v199, 0x80, v197
	ds_read_b128 v[216:219], v199
	s_waitcnt lgkmcnt(4)
	v_mfma_f32_32x32x16_bf16 v[128:143], v[220:223], v[224:227], v[128:143]
	v_xor_b32_e32 v144, 0xa0, v196
	v_add_u32_e32 v144, s60, v144
	ds_read_b128 v[220:223], v144
	v_xor_b32_e32 v199, 0xa0, v197
	ds_read_b128 v[224:227], v199
	s_waitcnt lgkmcnt(4)
	v_mfma_f32_32x32x16_bf16 v[128:143], v[188:191], v[200:203], v[128:143]
	v_xor_b32_e32 v144, 0xc0, v196
	v_add_u32_e32 v144, s60, v144
	ds_read_b128 v[188:191], v144
	v_xor_b32_e32 v199, 0xc0, v197
	ds_read_b128 v[200:203], v199
	s_waitcnt lgkmcnt(4)
	v_mfma_f32_32x32x16_bf16 v[156:171], v[204:207], v[216:219], 0
	v_xor_b32_e32 v144, 0xe0, v196
	v_add_u32_e32 v144, s60, v144
	ds_read_b128 v[204:207], v144
	v_xor_b32_e32 v199, 0xe0, v197
	ds_read_b128 v[216:219], v199
	s_waitcnt lgkmcnt(4)
	v_mfma_f32_32x32x16_bf16 v[156:171], v[220:223], v[224:227], v[156:171]
	v_add_u32_e32 v144, s60, v196
	ds_read_b128 v[220:223], v144 offset:8192
	ds_read_b128 v[224:227], v197
	v_exp_f32_e32 v128, v128
	v_exp_f32_e32 v129, v129
	v_exp_f32_e32 v130, v130
	v_exp_f32_e32 v131, v131
	v_exp_f32_e32 v132, v132
	s_waitcnt lgkmcnt(4)
	v_mfma_f32_32x32x16_bf16 v[156:171], v[188:191], v[200:203], v[156:171]
	v_xad_u32 v144, v196, 32, s60
	ds_read_b128 v[188:191], v144 offset:8192
	v_xor_b32_e32 v199, 32, v197
	ds_read_b128 v[200:203], v199
	v_exp_f32_e32 v133, v133
	v_exp_f32_e32 v134, v134
	v_exp_f32_e32 v135, v135
	v_exp_f32_e32 v136, v136
	v_exp_f32_e32 v137, v137
	s_waitcnt lgkmcnt(4)
	v_mfma_f32_32x32x16_bf16 v[156:171], v[204:207], v[216:219], v[156:171]
	v_xad_u32 v144, v196, 64, s60
	ds_read_b128 v[204:207], v144 offset:8192
	v_xor_b32_e32 v199, 64, v197
	ds_read_b128 v[216:219], v199
	v_exp_f32_e32 v138, v138
	v_exp_f32_e32 v139, v139
	v_exp_f32_e32 v140, v140
	v_exp_f32_e32 v141, v141
	v_exp_f32_e32 v142, v142
	s_waitcnt lgkmcnt(4)
	v_mfma_f32_32x32x16_bf16 v[172:187], v[220:223], v[224:227], 0
	v_xor_b32_e32 v144, 0x60, v196
	v_add_u32_e32 v144, s60, v144
	ds_read_b128 v[220:223], v144 offset:8192
	v_xor_b32_e32 v199, 0x60, v197
	ds_read_b128 v[224:227], v199
	v_exp_f32_e32 v143, v143
	v_add_f32_e32 v192, v128, v129
	v_add_f32_e32 v193, v130, v131
	v_add_f32_e32 v192, v192, v132
	v_add_f32_e32 v193, v193, v133
	v_add_f32_e32 v192, v192, v134
	v_add_f32_e32 v193, v193, v135
	v_add_f32_e32 v192, v192, v136
	v_add_f32_e32 v193, v193, v137
	v_add_f32_e32 v192, v192, v138
	s_waitcnt lgkmcnt(4)
	v_mfma_f32_32x32x16_bf16 v[172:187], v[188:191], v[200:203], v[172:187]
	v_xor_b32_e32 v144, 0x80, v196
	v_add_u32_e32 v144, s60, v144
	ds_read_b128 v[188:191], v144 offset:8192
	v_xor_b32_e32 v199, 0x80, v197
	ds_read_b128 v[200:203], v199
	v_add_f32_e32 v193, v193, v139
	v_add_f32_e32 v192, v192, v140
	v_add_f32_e32 v193, v193, v141
	v_add_f32_e32 v192, v192, v142
	v_add_f32_e32 v193, v193, v143
	v_add_f32_e32 v192, v192, v193
	v_add_f32_e32 v150, v150, v192
	v_cvt_pk_bf16_f32 v128, v128, v129
	v_cvt_pk_bf16_f32 v129, v130, v131
	v_cvt_pk_bf16_f32 v130, v132, v133
	v_cvt_pk_bf16_f32 v131, v134, v135
	s_waitcnt lgkmcnt(4)
	v_mfma_f32_32x32x16_bf16 v[172:187], v[204:207], v[216:219], v[172:187]
	v_xor_b32_e32 v144, 0xa0, v196
	v_add_u32_e32 v144, s60, v144
	ds_read_b128 v[204:207], v144 offset:8192
	v_xor_b32_e32 v199, 0xa0, v197
	ds_read_b128 v[216:219], v199
	v_cvt_pk_bf16_f32 v132, v136, v137
	v_cvt_pk_bf16_f32 v133, v138, v139
	v_cvt_pk_bf16_f32 v134, v140, v141
	v_cvt_pk_bf16_f32 v135, v142, v143
	v_exp_f32_e32 v156, v156
	v_exp_f32_e32 v157, v157
	v_exp_f32_e32 v158, v158
	s_waitcnt lgkmcnt(4)
	v_mfma_f32_32x32x16_bf16 v[172:187], v[220:223], v[224:227], v[172:187]
	v_xor_b32_e32 v144, 0xc0, v196
	v_add_u32_e32 v144, s60, v144
	ds_read_b128 v[220:223], v144 offset:8192
	v_xor_b32_e32 v199, 0xc0, v197
	ds_read_b128 v[224:227], v199
	v_exp_f32_e32 v159, v159
	v_exp_f32_e32 v160, v160
	v_exp_f32_e32 v161, v161
	v_exp_f32_e32 v162, v162
	v_exp_f32_e32 v163, v163
	s_waitcnt lgkmcnt(4)
	v_mfma_f32_32x32x16_bf16 v[228:243], v[188:191], v[200:203], 0
	v_xor_b32_e32 v144, 0xe0, v196
	v_add_u32_e32 v144, s60, v144
	ds_read_b128 v[188:191], v144 offset:8192
	v_xor_b32_e32 v199, 0xe0, v197
	ds_read_b128 v[200:203], v199
	v_exp_f32_e32 v164, v164
	v_exp_f32_e32 v165, v165
	v_exp_f32_e32 v166, v166
	v_exp_f32_e32 v167, v167
	v_exp_f32_e32 v168, v168
	s_waitcnt lgkmcnt(4)
	v_mfma_f32_32x32x16_bf16 v[228:243], v[204:207], v[216:219], v[228:243]
	v_add_u32_e32 v248, s60, v198
	v_xad_u32 v249, v198, 32, s60
	ds_read_b128 v[204:207], v248
	ds_read_b128 v[216:219], v249
	v_exp_f32_e32 v169, v169
	v_exp_f32_e32 v170, v170
	v_exp_f32_e32 v171, v171
	v_add_f32_e32 v192, v156, v157
	v_add_f32_e32 v193, v158, v159
	v_add_f32_e32 v192, v192, v160
	v_add_f32_e32 v193, v193, v161
	v_add_f32_e32 v192, v192, v162
	s_waitcnt lgkmcnt(4)
	v_mfma_f32_32x32x16_bf16 v[228:243], v[220:223], v[224:227], v[228:243]
	ds_read_b128 v[220:223], v248 offset:4096
	ds_read_b128 v[224:227], v249 offset:4096
	v_add_f32_e32 v193, v193, v163
	v_add_f32_e32 v192, v192, v164
	v_add_f32_e32 v193, v193, v165
	v_add_f32_e32 v192, v192, v166
	v_add_f32_e32 v193, v193, v167
	v_add_f32_e32 v192, v192, v168
	v_add_f32_e32 v193, v193, v169
	v_add_f32_e32 v192, v192, v170
	v_add_f32_e32 v193, v193, v171
	v_add_f32_e32 v192, v192, v193
	v_add_f32_e32 v151, v151, v192
	s_waitcnt lgkmcnt(4)
	v_mfma_f32_32x32x16_bf16 v[228:243], v[188:191], v[200:203], v[228:243]
	ds_read_b128 v[188:191], v248 offset:8192
	ds_read_b128 v[200:203], v249 offset:8192
	v_cvt_pk_bf16_f32 v156, v156, v157
	v_cvt_pk_bf16_f32 v157, v158, v159
	v_cvt_pk_bf16_f32 v158, v160, v161
	v_cvt_pk_bf16_f32 v159, v162, v163
	v_cvt_pk_bf16_f32 v160, v164, v165
	v_cvt_pk_bf16_f32 v161, v166, v167
	v_cvt_pk_bf16_f32 v162, v168, v169
	v_cvt_pk_bf16_f32 v163, v170, v171
	v_exp_f32_e32 v172, v172
	s_waitcnt lgkmcnt(4)
	v_mfma_f32_32x32x16_bf16 v[112:127], v[204:207], v[128:131], v[112:127]
	v_exp_f32_e32 v173, v173
	v_exp_f32_e32 v174, v174
	v_exp_f32_e32 v175, v175
	v_exp_f32_e32 v176, v176
	v_mfma_f32_32x32x16_bf16 v[96:111], v[204:207], v[156:159], v[96:111]
	v_exp_f32_e32 v177, v177
	v_exp_f32_e32 v178, v178
	v_exp_f32_e32 v179, v179
	v_exp_f32_e32 v180, v180
	v_mfma_f32_32x32x16_bf16 v[112:127], v[216:219], v[132:135], v[112:127]
	v_exp_f32_e32 v181, v181
	v_exp_f32_e32 v182, v182
	v_exp_f32_e32 v183, v183
	v_exp_f32_e32 v184, v184
	v_mfma_f32_32x32x16_bf16 v[96:111], v[216:219], v[160:163], v[96:111]
	ds_read_b128 v[204:207], v248 offset:12288
	ds_read_b128 v[216:219], v249 offset:12288
	v_exp_f32_e32 v185, v185
	v_exp_f32_e32 v186, v186
	v_exp_f32_e32 v187, v187
	v_add_f32_e32 v192, v172, v173
	v_add_f32_e32 v193, v174, v175
	v_add_f32_e32 v192, v192, v176
	s_waitcnt lgkmcnt(4)
	v_mfma_f32_32x32x16_bf16 v[80:95], v[220:223], v[128:131], v[80:95]
	v_add_f32_e32 v193, v193, v177
	v_add_f32_e32 v192, v192, v178
	v_add_f32_e32 v193, v193, v179
	v_add_f32_e32 v192, v192, v180
	v_add_f32_e32 v193, v193, v181
	v_add_f32_e32 v192, v192, v182
	v_add_f32_e32 v193, v193, v183
	v_add_f32_e32 v192, v192, v184
	v_add_f32_e32 v193, v193, v185
	v_mfma_f32_32x32x16_bf16 v[64:79], v[220:223], v[156:159], v[64:79]
	v_add_f32_e32 v192, v192, v186
	v_add_f32_e32 v193, v193, v187
	v_add_f32_e32 v192, v192, v193
	v_add_f32_e32 v150, v150, v192
	v_cvt_pk_bf16_f32 v172, v172, v173
	v_cvt_pk_bf16_f32 v173, v174, v175
	v_cvt_pk_bf16_f32 v174, v176, v177
	v_cvt_pk_bf16_f32 v175, v178, v179
	v_cvt_pk_bf16_f32 v176, v180, v181
	v_mfma_f32_32x32x16_bf16 v[80:95], v[224:227], v[132:135], v[80:95]
	v_cvt_pk_bf16_f32 v177, v182, v183
	v_cvt_pk_bf16_f32 v178, v184, v185
	v_cvt_pk_bf16_f32 v179, v186, v187
	v_exp_f32_e32 v228, v228
	v_exp_f32_e32 v229, v229
	v_exp_f32_e32 v230, v230
	v_mfma_f32_32x32x16_bf16 v[64:79], v[224:227], v[160:163], v[64:79]
	v_xad_u32 v248, v198, 64, s60
	v_xor_b32_e32 v249, 0x60, v198
	v_add_u32_e32 v249, s60, v249
	ds_read_b128 v[220:223], v248
	ds_read_b128 v[224:227], v249
	v_exp_f32_e32 v231, v231
	v_exp_f32_e32 v232, v232
	v_exp_f32_e32 v233, v233
	v_exp_f32_e32 v234, v234
	s_waitcnt lgkmcnt(4)
	v_mfma_f32_32x32x16_bf16 v[48:63], v[188:191], v[128:131], v[48:63]
	v_exp_f32_e32 v235, v235
	v_exp_f32_e32 v236, v236
	v_exp_f32_e32 v237, v237
	v_exp_f32_e32 v238, v238
	v_mfma_f32_32x32x16_bf16 v[32:47], v[188:191], v[156:159], v[32:47]
	v_exp_f32_e32 v239, v239
	v_exp_f32_e32 v240, v240
	v_exp_f32_e32 v241, v241
	v_exp_f32_e32 v242, v242
	v_mfma_f32_32x32x16_bf16 v[48:63], v[200:203], v[132:135], v[48:63]
	v_exp_f32_e32 v243, v243
	v_add_f32_e32 v192, v228, v229
	v_add_f32_e32 v193, v230, v231
	v_add_f32_e32 v192, v192, v232
	v_add_f32_e32 v193, v193, v233
	v_add_f32_e32 v192, v192, v234
	v_add_f32_e32 v193, v193, v235
	v_add_f32_e32 v192, v192, v236
	v_mfma_f32_32x32x16_bf16 v[32:47], v[200:203], v[160:163], v[32:47]
	ds_read_b128 v[188:191], v248 offset:4096
	ds_read_b128 v[200:203], v249 offset:4096
	v_add_f32_e32 v193, v193, v237
	v_add_f32_e32 v192, v192, v238
	v_add_f32_e32 v193, v193, v239
	v_add_f32_e32 v192, v192, v240
	v_add_f32_e32 v193, v193, v241
	v_add_f32_e32 v192, v192, v242
	v_add_f32_e32 v193, v193, v243
	v_add_f32_e32 v192, v192, v193
	v_add_f32_e32 v151, v151, v192
	s_waitcnt lgkmcnt(4)
	v_mfma_f32_32x32x16_bf16 v[16:31], v[204:207], v[128:131], v[16:31]
	v_cvt_pk_bf16_f32 v228, v228, v229
	v_cvt_pk_bf16_f32 v229, v230, v231
	v_cvt_pk_bf16_f32 v230, v232, v233
	v_cvt_pk_bf16_f32 v231, v234, v235
	v_cvt_pk_bf16_f32 v232, v236, v237
	v_cvt_pk_bf16_f32 v233, v238, v239
	v_cvt_pk_bf16_f32 v234, v240, v241
	v_cvt_pk_bf16_f32 v235, v242, v243
	v_mfma_f32_32x32x16_bf16 v[0:15], v[204:207], v[156:159], v[0:15]
	v_mfma_f32_32x32x16_bf16 v[16:31], v[216:219], v[132:135], v[16:31]
	v_mfma_f32_32x32x16_bf16 v[0:15], v[216:219], v[160:163], v[0:15]
	ds_read_b128 v[204:207], v248 offset:8192
	ds_read_b128 v[216:219], v249 offset:8192
	s_waitcnt lgkmcnt(4)
	v_mfma_f32_32x32x16_bf16 v[112:127], v[220:223], v[172:175], v[112:127]
	v_mfma_f32_32x32x16_bf16 v[96:111], v[220:223], v[228:231], v[96:111]
	s_cbranch_vccnz .Lattn_d0
	v_lshl_add_u64 v[244:245], s[54:55], 0, v[146:147]
	s_add_i32 m0, s27, s61
	s_nop 0
	global_load_lds_dwordx4 v[244:245], off
.Lattn_d0:
	v_mfma_f32_32x32x16_bf16 v[112:127], v[224:227], v[176:179], v[112:127]
	v_mfma_f32_32x32x16_bf16 v[96:111], v[224:227], v[232:235], v[96:111]
	ds_read_b128 v[220:223], v248 offset:12288
	ds_read_b128 v[224:227], v249 offset:12288
	s_waitcnt lgkmcnt(4)
	v_mfma_f32_32x32x16_bf16 v[80:95], v[188:191], v[172:175], v[80:95]
	s_cbranch_vccnz .Lattn_d1
	v_lshl_add_u64 v[244:245], s[54:55], 0, v[152:153]
	s_add_i32 m0, m0, 0x4000
	s_nop 0
	global_load_lds_dwordx4 v[244:245], off
.Lattn_d1:
	v_mfma_f32_32x32x16_bf16 v[64:79], v[188:191], v[228:231], v[64:79]
	v_mfma_f32_32x32x16_bf16 v[80:95], v[200:203], v[176:179], v[80:95]
	v_mfma_f32_32x32x16_bf16 v[64:79], v[200:203], v[232:235], v[64:79]
	s_cbranch_vccnz .Lattn_d2
	v_lshl_add_u64 v[244:245], s[54:55], 0, v[148:149]
	s_add_i32 m0, m0, 0xffffc400
	s_nop 0
	global_load_lds_dwordx4 v[244:245], off
.Lattn_d2:
	s_waitcnt lgkmcnt(2)
	v_mfma_f32_32x32x16_bf16 v[48:63], v[204:207], v[172:175], v[48:63]
	v_mfma_f32_32x32x16_bf16 v[32:47], v[204:207], v[228:231], v[32:47]
	v_mfma_f32_32x32x16_bf16 v[48:63], v[216:219], v[176:179], v[48:63]
	s_cbranch_vccnz .Lattn_d3
	v_lshl_add_u64 v[244:245], s[54:55], 0, v[154:155]
	s_add_i32 m0, m0, 0x4000
	s_nop 0
	global_load_lds_dwordx4 v[244:245], off
.Lattn_d3:
	v_mfma_f32_32x32x16_bf16 v[32:47], v[216:219], v[232:235], v[32:47]
	s_waitcnt lgkmcnt(0)
	v_mfma_f32_32x32x16_bf16 v[16:31], v[220:223], v[172:175], v[16:31]
	v_mfma_f32_32x32x16_bf16 v[0:15], v[220:223], v[228:231], v[0:15]
	v_mfma_f32_32x32x16_bf16 v[16:31], v[224:227], v[176:179], v[16:31]
	v_mfma_f32_32x32x16_bf16 v[0:15], v[224:227], v[232:235], v[0:15]
	s_mov_b64 s[92:93], -1
	s_and_b64 vcc, exec, s[86:87]
	s_cbranch_vccnz .LBB0_38
